# lever 1/2 on the layer-0 K-tile epilogue: the 32 key-sum columns are reduced over the lanes in batched butterfly stages (16 ds_bpermute per LDS round trip) instead of 160 serialized bpermute-wait-add
# speedup vs baseline: 1.0052x; 1.0052x over previous
.LBB0_246:
	v_mov_b32_e32 v128, s75
	v_mov_b32_e32 v129, s13
	v_cmp_lt_i32_e32 vcc, s81, v164
	v_mov_b32_e32 v130, s12
	v_and_b32_e32 v131, 64, v186
	v_cndmask_b32_e32 v129, v128, v129, vcc
	v_mov_b32_e32 v128, s74
	v_cndmask_b32_e32 v128, v128, v130, vcc
	v_xor_b32_e32 v130, 32, v186
	v_add_u32_e32 v190, 64, v131
	v_lshlrev_b32_e32 v160, 4, v187
	v_cmp_lt_i32_e64 s[4:5], v130, v190
	v_lshl_add_u64 v[128:129], v[128:129], 0, v[160:161]
	v_mov_b32_e32 v176, v65
	v_cndmask_b32_e64 v130, v186, v130, s[4:5]
	v_lshlrev_b32_e32 v191, 2, v130
	global_load_dwordx4 v[148:151], v[128:129], off
	global_load_dwordx4 v[144:147], v[128:129], off offset:32
	global_load_dwordx4 v[152:155], v[128:129], off offset:64
	global_load_dwordx4 v[156:159], v[128:129], off offset:96
	global_load_dwordx4 v[140:143], v[128:129], off offset:128
	global_load_dwordx4 v[136:139], v[128:129], off offset:160
	global_load_dwordx4 v[132:135], v[128:129], off offset:192
	s_nop 0
	global_load_dwordx4 v[128:131], v[128:129], off offset:224
	v_mov_b32_e32 v177, v97
	v_mov_b32_e32 v174, v64
	v_mov_b32_e32 v175, v96
	v_pk_mul_f32 v[176:177], v[176:177], v[176:177]
	v_pk_mul_f32 v[172:173], v[118:119], v[118:119]
	v_pk_fma_f32 v[174:175], v[174:175], v[174:175], v[176:177]
	v_mov_b32_e32 v176, v66
	v_mov_b32_e32 v177, v98
	v_pk_fma_f32 v[174:175], v[176:177], v[176:177], v[174:175]
	v_mov_b32_e32 v176, v67
	v_mov_b32_e32 v177, v99
	v_pk_fma_f32 v[174:175], v[176:177], v[176:177], v[174:175]
	v_mov_b32_e32 v176, v68
	v_mov_b32_e32 v177, v100
	v_pk_fma_f32 v[174:175], v[176:177], v[176:177], v[174:175]
	v_mov_b32_e32 v176, v69
	v_mov_b32_e32 v177, v101
	v_pk_fma_f32 v[174:175], v[176:177], v[176:177], v[174:175]
	v_mov_b32_e32 v176, v70
	v_mov_b32_e32 v177, v102
	v_pk_fma_f32 v[174:175], v[176:177], v[176:177], v[174:175]
	v_mov_b32_e32 v176, v71
	v_mov_b32_e32 v177, v103
	v_pk_fma_f32 v[174:175], v[176:177], v[176:177], v[174:175]
	v_mov_b32_e32 v176, v72
	v_mov_b32_e32 v177, v104
	v_pk_fma_f32 v[174:175], v[176:177], v[176:177], v[174:175]
	v_mov_b32_e32 v176, v73
	v_mov_b32_e32 v177, v105
	v_pk_fma_f32 v[174:175], v[176:177], v[176:177], v[174:175]
	v_mov_b32_e32 v176, v74
	v_mov_b32_e32 v177, v106
	v_pk_fma_f32 v[174:175], v[176:177], v[176:177], v[174:175]
	v_mov_b32_e32 v176, v75
	v_mov_b32_e32 v177, v107
	v_pk_fma_f32 v[174:175], v[176:177], v[176:177], v[174:175]
	v_mov_b32_e32 v176, v76
	v_mov_b32_e32 v177, v108
	v_pk_fma_f32 v[174:175], v[176:177], v[176:177], v[174:175]
	v_mov_b32_e32 v176, v77
	v_mov_b32_e32 v177, v109
	v_pk_fma_f32 v[174:175], v[176:177], v[176:177], v[174:175]
	v_mov_b32_e32 v176, v78
	v_mov_b32_e32 v177, v110
	v_pk_fma_f32 v[174:175], v[176:177], v[176:177], v[174:175]
	v_mov_b32_e32 v176, v79
	v_mov_b32_e32 v177, v111
	v_pk_fma_f32 v[174:175], v[176:177], v[176:177], v[174:175]
	v_mov_b32_e32 v176, v80
	v_mov_b32_e32 v177, v112
	v_pk_fma_f32 v[174:175], v[176:177], v[176:177], v[174:175]
	v_mov_b32_e32 v176, v81
	v_mov_b32_e32 v177, v113
	v_pk_fma_f32 v[174:175], v[176:177], v[176:177], v[174:175]
	v_mov_b32_e32 v176, v82
	v_mov_b32_e32 v177, v114
	v_pk_fma_f32 v[174:175], v[176:177], v[176:177], v[174:175]
	v_mov_b32_e32 v176, v83
	v_mov_b32_e32 v177, v115
	v_pk_fma_f32 v[174:175], v[176:177], v[176:177], v[174:175]
	v_mov_b32_e32 v176, v84
	v_mov_b32_e32 v177, v116
	v_pk_mul_f32 v[192:193], v[86:87], v[86:87]
	v_pk_fma_f32 v[174:175], v[176:177], v[176:177], v[174:175]
	v_mov_b32_e32 v176, v85
	v_mov_b32_e32 v177, v117
	v_pk_fma_f32 v[174:175], v[176:177], v[176:177], v[174:175]
	v_mov_b32_e32 v176, v192
	v_mov_b32_e32 v177, v172
	v_pk_mul_f32 v[170:171], v[120:121], v[120:121]
	v_pk_mul_f32 v[184:185], v[88:89], v[88:89]
	v_pk_add_f32 v[174:175], v[176:177], v[174:175]
	v_mov_b32_e32 v172, v193
	v_pk_add_f32 v[172:173], v[172:173], v[174:175]
	v_mov_b32_e32 v174, v184
	v_mov_b32_e32 v175, v170
	v_pk_mul_f32 v[168:169], v[122:123], v[122:123]
	v_pk_mul_f32 v[182:183], v[90:91], v[90:91]
	v_pk_add_f32 v[172:173], v[174:175], v[172:173]
	v_mov_b32_e32 v170, v185
	v_pk_add_f32 v[170:171], v[170:171], v[172:173]
	v_mov_b32_e32 v172, v182
	v_mov_b32_e32 v173, v168
	v_pk_mul_f32 v[166:167], v[124:125], v[124:125]
	v_pk_mul_f32 v[180:181], v[92:93], v[92:93]
	v_pk_add_f32 v[170:171], v[172:173], v[170:171]
	v_mov_b32_e32 v168, v183
	v_pk_add_f32 v[168:169], v[168:169], v[170:171]
	v_mov_b32_e32 v170, v180
	v_mov_b32_e32 v171, v166
	v_pk_mul_f32 v[162:163], v[126:127], v[126:127]
	v_pk_mul_f32 v[178:179], v[94:95], v[94:95]
	v_pk_add_f32 v[168:169], v[170:171], v[168:169]
	v_mov_b32_e32 v166, v181
	v_pk_add_f32 v[166:167], v[166:167], v[168:169]
	v_mov_b32_e32 v168, v178
	v_mov_b32_e32 v169, v162
	v_pk_add_f32 v[166:167], v[168:169], v[166:167]
	v_mov_b32_e32 v162, v179
	v_pk_add_f32 v[162:163], v[162:163], v[166:167]
	ds_bpermute_b32 v167, v191, v163
	ds_bpermute_b32 v166, v191, v162
	v_mov_b64_e32 v[182:183], s[38:39]
	v_ashrrev_i32_e32 v165, 31, v164
	v_lshl_add_u64 v[180:181], v[164:165], 1, s[8:9]
	v_lshl_or_b32 v192, v188, 1, v189
	s_waitcnt lgkmcnt(0)
	v_pk_add_f32 v[162:163], v[162:163], v[166:167]
	s_nop 0
	v_pk_fma_f32 v[184:185], v[162:163], s[36:37], v[182:183] op_sel_hi:[1,0,0]
	s_nop 0
	v_mul_f32_e32 v162, 0x4b800000, v185
	v_cmp_gt_f32_e64 s[4:5], s82, v185
	s_nop 1
	v_cndmask_b32_e64 v162, v185, v162, s[4:5]
	v_rsq_f32_e32 v165, v162
	v_mad_i64_i32 v[162:163], s[62:63], v192, s80, v[180:181]
	v_lshl_add_u64 v[202:203], v[162:163], 0, v[160:161]
	v_mul_f32_e32 v162, 0x45800000, v165
	v_cndmask_b32_e64 v204, v165, v162, s[4:5]
	v_pk_mul_f32 v[96:97], v[96:97], v[204:205] op_sel_hi:[1,0]
	v_cmp_gt_f32_e64 s[4:5], s82, v184
	s_waitcnt vmcnt(7)
	v_pk_mul_f32 v[178:179], v[148:149], v[96:97]
	v_pk_mul_f32 v[96:97], v[98:99], v[204:205] op_sel_hi:[1,0]
	v_cvt_pk_bf16_f32 v194, v178, v179
	v_pk_mul_f32 v[176:177], v[150:151], v[96:97]
	v_pk_mul_f32 v[96:97], v[100:101], v[204:205] op_sel_hi:[1,0]
	v_cvt_pk_bf16_f32 v195, v176, v177
	s_waitcnt vmcnt(6)
	v_pk_mul_f32 v[174:175], v[144:145], v[96:97]
	v_pk_mul_f32 v[96:97], v[102:103], v[204:205] op_sel_hi:[1,0]
	v_cvt_pk_bf16_f32 v196, v174, v175
	v_pk_mul_f32 v[172:173], v[146:147], v[96:97]
	v_pk_mul_f32 v[96:97], v[104:105], v[204:205] op_sel_hi:[1,0]
	v_cvt_pk_bf16_f32 v197, v172, v173
	s_waitcnt vmcnt(5)
	v_pk_mul_f32 v[170:171], v[152:153], v[96:97]
	v_pk_mul_f32 v[96:97], v[106:107], v[204:205] op_sel_hi:[1,0]
	v_cvt_pk_bf16_f32 v198, v170, v171
	v_pk_mul_f32 v[168:169], v[154:155], v[96:97]
	v_pk_mul_f32 v[96:97], v[108:109], v[204:205] op_sel_hi:[1,0]
	v_cvt_pk_bf16_f32 v199, v168, v169
	s_waitcnt vmcnt(4)
	v_pk_mul_f32 v[166:167], v[156:157], v[96:97]
	v_pk_mul_f32 v[96:97], v[110:111], v[204:205] op_sel_hi:[1,0]
	v_cvt_pk_bf16_f32 v200, v166, v167
	v_pk_mul_f32 v[162:163], v[158:159], v[96:97]
	v_pk_mul_f32 v[96:97], v[112:113], v[204:205] op_sel_hi:[1,0]
	v_cvt_pk_bf16_f32 v201, v162, v163
	s_waitcnt vmcnt(3)
	v_pk_mul_f32 v[110:111], v[140:141], v[96:97]
	v_pk_mul_f32 v[96:97], v[114:115], v[204:205] op_sel_hi:[1,0]
	v_cvt_pk_bf16_f32 v112, v110, v111
	v_pk_mul_f32 v[108:109], v[142:143], v[96:97]
	v_pk_mul_f32 v[96:97], v[116:117], v[204:205] op_sel_hi:[1,0]
	v_cvt_pk_bf16_f32 v113, v108, v109
	s_waitcnt vmcnt(2)
	v_pk_mul_f32 v[106:107], v[136:137], v[96:97]
	v_pk_mul_f32 v[96:97], v[118:119], v[204:205] op_sel_hi:[1,0]
	v_cvt_pk_bf16_f32 v114, v106, v107
	v_pk_mul_f32 v[104:105], v[138:139], v[96:97]
	v_permlane32_swap_b32_e32 v194, v196
	v_cvt_pk_bf16_f32 v115, v104, v105
	v_permlane32_swap_b32_e32 v195, v197
	v_permlane32_swap_b32_e32 v112, v114
	v_permlane32_swap_b32_e32 v113, v115
	v_permlane32_swap_b32_e32 v198, v200
	v_permlane32_swap_b32_e32 v199, v201
	global_store_dwordx4 v[202:203], v[194:197], off
	global_store_dwordx4 v[202:203], v[198:201], off offset:32
	global_store_dwordx4 v[202:203], v[112:115], off offset:64
	v_pk_mul_f32 v[96:97], v[120:121], v[204:205] op_sel_hi:[1,0]
	v_pk_mul_f32 v[200:201], v[26:27], v[26:27]
	v_mul_f32_e32 v112, 0x4b800000, v184
	v_cndmask_b32_e64 v112, v184, v112, s[4:5]
	v_rsq_f32_e32 v112, v112
	s_waitcnt vmcnt(4)
	v_pk_mul_f32 v[102:103], v[132:133], v[96:97]
	v_pk_mul_f32 v[96:97], v[122:123], v[204:205] op_sel_hi:[1,0]
	v_cvt_pk_bf16_f32 v116, v102, v103
	v_mul_f32_e32 v113, 0x45800000, v112
	v_cndmask_b32_e64 v194, v112, v113, s[4:5]
	v_pk_mul_f32 v[100:101], v[134:135], v[96:97]
	v_pk_mul_f32 v[96:97], v[124:125], v[204:205] op_sel_hi:[1,0]
	v_pk_mul_f32 v[64:65], v[64:65], v[194:195] op_sel_hi:[1,0]
	s_waitcnt vmcnt(3)
	v_pk_mul_f32 v[98:99], v[128:129], v[96:97]
	v_pk_mul_f32 v[96:97], v[126:127], v[204:205] op_sel_hi:[1,0]
	v_pk_mul_f32 v[126:127], v[148:149], v[64:65]
	v_pk_mul_f32 v[64:65], v[66:67], v[194:195] op_sel_hi:[1,0]
	v_pk_mul_f32 v[66:67], v[68:69], v[194:195] op_sel_hi:[1,0]
	v_or_b32_e32 v112, 1, v192
	v_pk_mul_f32 v[122:123], v[144:145], v[66:67]
	v_pk_mul_f32 v[66:67], v[70:71], v[194:195] op_sel_hi:[1,0]
	v_pk_mul_f32 v[124:125], v[150:151], v[64:65]
	v_pk_mul_f32 v[120:121], v[146:147], v[66:67]
	v_pk_mul_f32 v[96:97], v[130:131], v[96:97]
	v_mad_i64_i32 v[184:185], s[4:5], v112, s80, v[180:181]
	v_cvt_pk_bf16_f32 v64, v126, v127
	v_cvt_pk_bf16_f32 v65, v124, v125
	v_cvt_pk_bf16_f32 v66, v122, v123
	v_cvt_pk_bf16_f32 v67, v120, v121
	v_cvt_pk_bf16_f32 v117, v100, v101
	v_cvt_pk_bf16_f32 v118, v98, v99
	v_cvt_pk_bf16_f32 v119, v96, v97
	v_permlane32_swap_b32_e32 v64, v66
	v_permlane32_swap_b32_e32 v65, v67
	v_lshl_add_u64 v[184:185], v[184:185], 0, v[160:161]
	v_permlane32_swap_b32_e32 v116, v118
	v_permlane32_swap_b32_e32 v117, v119
	v_pk_mul_f32 v[68:69], v[72:73], v[194:195] op_sel_hi:[1,0]
	v_pk_mul_f32 v[70:71], v[76:77], v[194:195] op_sel_hi:[1,0]
	global_store_dwordx4 v[184:185], v[64:67], off
	global_store_dwordx4 v[202:203], v[116:119], off offset:96
	v_pk_mul_f32 v[114:115], v[156:157], v[70:71]
	v_pk_mul_f32 v[64:65], v[80:81], v[194:195] op_sel_hi:[1,0]
	v_pk_mul_f32 v[118:119], v[152:153], v[68:69]
	v_pk_mul_f32 v[68:69], v[74:75], v[194:195] op_sel_hi:[1,0]
	v_pk_mul_f32 v[70:71], v[78:79], v[194:195] op_sel_hi:[1,0]
	v_pk_mul_f32 v[78:79], v[140:141], v[64:65]
	v_pk_mul_f32 v[64:65], v[82:83], v[194:195] op_sel_hi:[1,0]
	v_pk_mul_f32 v[116:117], v[154:155], v[68:69]
	v_pk_mul_f32 v[112:113], v[158:159], v[70:71]
	v_pk_mul_f32 v[76:77], v[142:143], v[64:65]
	v_pk_mul_f32 v[64:65], v[84:85], v[194:195] op_sel_hi:[1,0]
	v_cvt_pk_bf16_f32 v68, v118, v119
	v_cvt_pk_bf16_f32 v69, v116, v117
	v_cvt_pk_bf16_f32 v70, v114, v115
	v_cvt_pk_bf16_f32 v71, v112, v113
	v_pk_mul_f32 v[74:75], v[136:137], v[64:65]
	v_pk_mul_f32 v[64:65], v[86:87], v[194:195] op_sel_hi:[1,0]
	v_permlane32_swap_b32_e32 v68, v70
	v_permlane32_swap_b32_e32 v69, v71
	v_pk_mul_f32 v[72:73], v[138:139], v[64:65]
	v_pk_mul_f32 v[64:65], v[88:89], v[194:195] op_sel_hi:[1,0]
	global_store_dwordx4 v[184:185], v[68:71], off offset:32
	v_pk_mul_f32 v[204:205], v[22:23], v[22:23]
	v_pk_mul_f32 v[202:203], v[24:25], v[24:25]
	v_pk_mul_f32 v[70:71], v[132:133], v[64:65]
	v_pk_mul_f32 v[64:65], v[90:91], v[194:195] op_sel_hi:[1,0]
	v_pk_mul_f32 v[90:91], v[56:57], v[56:57]
	v_pk_mul_f32 v[68:69], v[134:135], v[64:65]
	v_pk_mul_f32 v[64:65], v[92:93], v[194:195] op_sel_hi:[1,0]
	v_pk_mul_f32 v[92:93], v[54:55], v[54:55]
	v_pk_mul_f32 v[66:67], v[128:129], v[64:65]
	v_pk_mul_f32 v[64:65], v[94:95], v[194:195] op_sel_hi:[1,0]
	v_mov_b32_e32 v194, v1
	v_mov_b32_e32 v195, v33
	v_mov_b32_e32 v94, v0
	v_mov_b32_e32 v95, v32
	v_pk_mul_f32 v[194:195], v[194:195], v[194:195]
	v_cvt_pk_bf16_f32 v80, v78, v79
	v_pk_fma_f32 v[94:95], v[94:95], v[94:95], v[194:195]
	v_mov_b32_e32 v194, v2
	v_mov_b32_e32 v195, v34
	v_pk_fma_f32 v[94:95], v[194:195], v[194:195], v[94:95]
	v_mov_b32_e32 v194, v3
	v_mov_b32_e32 v195, v35
	v_pk_fma_f32 v[94:95], v[194:195], v[194:195], v[94:95]
	v_mov_b32_e32 v194, v4
	v_mov_b32_e32 v195, v36
	v_pk_fma_f32 v[94:95], v[194:195], v[194:195], v[94:95]
	v_mov_b32_e32 v194, v5
	v_mov_b32_e32 v195, v37
	v_pk_fma_f32 v[94:95], v[194:195], v[194:195], v[94:95]
	v_mov_b32_e32 v194, v6
	v_mov_b32_e32 v195, v38
	v_pk_fma_f32 v[94:95], v[194:195], v[194:195], v[94:95]
	v_mov_b32_e32 v194, v7
	v_mov_b32_e32 v195, v39
	v_pk_fma_f32 v[94:95], v[194:195], v[194:195], v[94:95]
	v_mov_b32_e32 v194, v8
	v_mov_b32_e32 v195, v40
	v_pk_fma_f32 v[94:95], v[194:195], v[194:195], v[94:95]
	v_mov_b32_e32 v194, v9
	v_mov_b32_e32 v195, v41
	v_pk_fma_f32 v[94:95], v[194:195], v[194:195], v[94:95]
	v_mov_b32_e32 v194, v10
	v_mov_b32_e32 v195, v42
	v_pk_fma_f32 v[94:95], v[194:195], v[194:195], v[94:95]
	v_mov_b32_e32 v194, v11
	v_mov_b32_e32 v195, v43
	v_pk_fma_f32 v[94:95], v[194:195], v[194:195], v[94:95]
	v_mov_b32_e32 v194, v12
	v_mov_b32_e32 v195, v44
	v_pk_fma_f32 v[94:95], v[194:195], v[194:195], v[94:95]
	v_mov_b32_e32 v194, v13
	v_mov_b32_e32 v195, v45
	v_pk_fma_f32 v[94:95], v[194:195], v[194:195], v[94:95]
	v_mov_b32_e32 v194, v14
	v_mov_b32_e32 v195, v46
	v_pk_fma_f32 v[94:95], v[194:195], v[194:195], v[94:95]
	v_mov_b32_e32 v194, v15
	v_mov_b32_e32 v195, v47
	v_pk_fma_f32 v[94:95], v[194:195], v[194:195], v[94:95]
	v_mov_b32_e32 v194, v16
	v_mov_b32_e32 v195, v48
	v_pk_fma_f32 v[94:95], v[194:195], v[194:195], v[94:95]
	v_mov_b32_e32 v194, v17
	v_mov_b32_e32 v195, v49
	v_pk_fma_f32 v[94:95], v[194:195], v[194:195], v[94:95]
	v_mov_b32_e32 v194, v18
	v_mov_b32_e32 v195, v50
	v_pk_fma_f32 v[94:95], v[194:195], v[194:195], v[94:95]
	v_mov_b32_e32 v194, v19
	v_mov_b32_e32 v195, v51
	v_pk_fma_f32 v[94:95], v[194:195], v[194:195], v[94:95]
	v_mov_b32_e32 v194, v20
	v_mov_b32_e32 v195, v52
	v_pk_fma_f32 v[94:95], v[194:195], v[194:195], v[94:95]
	v_mov_b32_e32 v194, v21
	v_mov_b32_e32 v195, v53
	v_pk_fma_f32 v[94:95], v[194:195], v[194:195], v[94:95]
	v_mov_b32_e32 v194, v204
	v_mov_b32_e32 v195, v92
	v_pk_add_f32 v[94:95], v[194:195], v[94:95]
	v_mov_b32_e32 v92, v205
	v_pk_add_f32 v[92:93], v[92:93], v[94:95]
	v_mov_b32_e32 v94, v202
	v_mov_b32_e32 v95, v90
	v_cvt_pk_bf16_f32 v81, v76, v77
	v_cvt_pk_bf16_f32 v82, v74, v75
	v_cvt_pk_bf16_f32 v83, v72, v73
	v_pk_mul_f32 v[88:89], v[58:59], v[58:59]
	v_pk_add_f32 v[92:93], v[94:95], v[92:93]
	v_mov_b32_e32 v90, v203
	v_permlane32_swap_b32_e32 v80, v82
	v_permlane32_swap_b32_e32 v81, v83
	v_pk_add_f32 v[90:91], v[90:91], v[92:93]
	v_mov_b32_e32 v92, v200
	v_mov_b32_e32 v93, v88
	global_store_dwordx4 v[184:185], v[80:83], off offset:64
	v_pk_mul_f32 v[198:199], v[28:29], v[28:29]
	v_pk_add_f32 v[90:91], v[92:93], v[90:91]
	v_pk_mul_f32 v[82:83], v[60:61], v[60:61]
	v_mov_b32_e32 v88, v201
	v_pk_add_f32 v[88:89], v[88:89], v[90:91]
	v_mov_b32_e32 v90, v198
	v_mov_b32_e32 v91, v82
	v_pk_mul_f32 v[80:81], v[62:63], v[62:63]
	v_pk_mul_f32 v[196:197], v[30:31], v[30:31]
	v_pk_add_f32 v[88:89], v[90:91], v[88:89]
	v_mov_b32_e32 v82, v199
	v_pk_add_f32 v[82:83], v[82:83], v[88:89]
	v_mov_b32_e32 v88, v196
	v_mov_b32_e32 v89, v80
	v_pk_add_f32 v[82:83], v[88:89], v[82:83]
	v_mov_b32_e32 v80, v197
	v_pk_add_f32 v[80:81], v[80:81], v[82:83]
	ds_bpermute_b32 v83, v191, v81
	ds_bpermute_b32 v82, v191, v80
	v_pk_mul_f32 v[64:65], v[130:131], v[64:65]
	v_cvt_pk_bf16_f32 v84, v70, v71
	v_cvt_pk_bf16_f32 v85, v68, v69
	v_cvt_pk_bf16_f32 v86, v66, v67
	s_waitcnt lgkmcnt(0)
	v_pk_add_f32 v[80:81], v[80:81], v[82:83]
	v_cvt_pk_bf16_f32 v87, v64, v65
	v_pk_fma_f32 v[182:183], v[80:81], s[36:37], v[182:183] op_sel_hi:[1,0,0]
	v_permlane32_swap_b32_e32 v84, v86
	v_mul_f32_e32 v80, 0x4b800000, v183
	v_cmp_gt_f32_e64 s[4:5], s82, v183
	v_permlane32_swap_b32_e32 v85, v87
	s_nop 0
	v_cndmask_b32_e64 v80, v183, v80, s[4:5]
	v_rsq_f32_e32 v82, v80
	global_store_dwordx4 v[184:185], v[84:87], off offset:96
	s_nop 1
	v_or_b32_e32 v84, 64, v192
	v_mad_i64_i32 v[80:81], s[62:63], v84, s80, v[180:181]
	v_lshl_add_u64 v[184:185], v[80:81], 0, v[160:161]
	v_mul_f32_e32 v80, 0x45800000, v82
	v_cndmask_b32_e64 v194, v82, v80, s[4:5]
	v_pk_mul_f32 v[32:33], v[32:33], v[194:195] op_sel_hi:[1,0]
	v_cmp_gt_f32_e64 s[4:5], s82, v182
	v_pk_mul_f32 v[94:95], v[148:149], v[32:33]
	v_pk_mul_f32 v[32:33], v[34:35], v[194:195] op_sel_hi:[1,0]
	v_pk_mul_f32 v[34:35], v[36:37], v[194:195] op_sel_hi:[1,0]
	v_pk_mul_f32 v[92:93], v[150:151], v[32:33]
	v_pk_mul_f32 v[90:91], v[144:145], v[34:35]
	v_pk_mul_f32 v[34:35], v[38:39], v[194:195] op_sel_hi:[1,0]
	v_cvt_pk_bf16_f32 v32, v94, v95
	v_pk_mul_f32 v[88:89], v[146:147], v[34:35]
	v_cvt_pk_bf16_f32 v33, v92, v93
	v_cvt_pk_bf16_f32 v34, v90, v91
	v_cvt_pk_bf16_f32 v35, v88, v89
	s_nop 0
	v_permlane32_swap_b32_e32 v32, v34
	v_permlane32_swap_b32_e32 v33, v35
	v_pk_mul_f32 v[38:39], v[44:45], v[194:195] op_sel_hi:[1,0]
	global_store_dwordx4 v[184:185], v[32:35], off
	v_pk_mul_f32 v[82:83], v[156:157], v[38:39]
	v_pk_mul_f32 v[38:39], v[46:47], v[194:195] op_sel_hi:[1,0]
	v_pk_mul_f32 v[32:33], v[48:49], v[194:195] op_sel_hi:[1,0]
	v_pk_mul_f32 v[36:37], v[40:41], v[194:195] op_sel_hi:[1,0]
	v_pk_mul_f32 v[46:47], v[140:141], v[32:33]
	v_pk_mul_f32 v[32:33], v[50:51], v[194:195] op_sel_hi:[1,0]
	v_pk_mul_f32 v[86:87], v[152:153], v[36:37]
	v_pk_mul_f32 v[44:45], v[142:143], v[32:33]
	v_pk_mul_f32 v[32:33], v[52:53], v[194:195] op_sel_hi:[1,0]
	v_pk_mul_f32 v[36:37], v[42:43], v[194:195] op_sel_hi:[1,0]
	v_pk_mul_f32 v[42:43], v[136:137], v[32:33]
	v_pk_mul_f32 v[32:33], v[54:55], v[194:195] op_sel_hi:[1,0]
	v_cvt_pk_bf16_f32 v48, v46, v47
	v_pk_mul_f32 v[40:41], v[138:139], v[32:33]
	v_cvt_pk_bf16_f32 v49, v44, v45
	v_cvt_pk_bf16_f32 v50, v42, v43
	v_cvt_pk_bf16_f32 v51, v40, v41
	s_nop 0
	v_permlane32_swap_b32_e32 v48, v50
	v_permlane32_swap_b32_e32 v49, v51
	global_store_dwordx4 v[184:185], v[48:51], off offset:64
	v_pk_mul_f32 v[84:85], v[154:155], v[36:37]
	v_pk_mul_f32 v[80:81], v[158:159], v[38:39]
	v_mul_f32_e32 v48, 0x4b800000, v182
	v_cndmask_b32_e64 v48, v182, v48, s[4:5]
	v_rsq_f32_e32 v48, v48
	v_cvt_pk_bf16_f32 v36, v86, v87
	v_cvt_pk_bf16_f32 v37, v84, v85
	v_cvt_pk_bf16_f32 v38, v82, v83
	v_cvt_pk_bf16_f32 v39, v80, v81
	s_nop 0
	v_permlane32_swap_b32_e32 v36, v38
	v_permlane32_swap_b32_e32 v37, v39
	v_pk_mul_f32 v[32:33], v[56:57], v[194:195] op_sel_hi:[1,0]
	v_mul_f32_e32 v49, 0x45800000, v48
	global_store_dwordx4 v[184:185], v[36:39], off offset:32
	v_cndmask_b32_e64 v182, v48, v49, s[4:5]
	v_pk_mul_f32 v[0:1], v[0:1], v[182:183] op_sel_hi:[1,0]
	v_pk_mul_f32 v[38:39], v[132:133], v[32:33]
	v_pk_mul_f32 v[32:33], v[58:59], v[194:195] op_sel_hi:[1,0]
	v_or_b32_e32 v48, 0x41, v192
	v_pk_mul_f32 v[36:37], v[134:135], v[32:33]
	v_pk_mul_f32 v[32:33], v[60:61], v[194:195] op_sel_hi:[1,0]
	v_mad_i64_i32 v[180:181], s[4:5], v48, s80, v[180:181]
	v_pk_mul_f32 v[34:35], v[128:129], v[32:33]
	v_pk_mul_f32 v[32:33], v[62:63], v[194:195] op_sel_hi:[1,0]
	v_pk_mul_f32 v[62:63], v[148:149], v[0:1]
	v_pk_mul_f32 v[0:1], v[2:3], v[182:183] op_sel_hi:[1,0]
	v_pk_mul_f32 v[2:3], v[4:5], v[182:183] op_sel_hi:[1,0]
	v_pk_mul_f32 v[60:61], v[150:151], v[0:1]
	v_pk_mul_f32 v[58:59], v[144:145], v[2:3]
	v_pk_mul_f32 v[2:3], v[6:7], v[182:183] op_sel_hi:[1,0]
	v_cvt_pk_bf16_f32 v0, v62, v63
	v_pk_mul_f32 v[56:57], v[146:147], v[2:3]
	v_cvt_pk_bf16_f32 v1, v60, v61
	v_cvt_pk_bf16_f32 v2, v58, v59
	v_cvt_pk_bf16_f32 v3, v56, v57
	v_pk_mul_f32 v[32:33], v[130:131], v[32:33]
	v_permlane32_swap_b32_e32 v0, v2
	v_permlane32_swap_b32_e32 v1, v3
	v_lshl_add_u64 v[144:145], v[180:181], 0, v[160:161]
	v_cvt_pk_bf16_f32 v52, v38, v39
	v_cvt_pk_bf16_f32 v53, v36, v37
	v_cvt_pk_bf16_f32 v54, v34, v35
	v_cvt_pk_bf16_f32 v55, v32, v33
	global_store_dwordx4 v[144:145], v[0:3], off
	v_permlane32_swap_b32_e32 v52, v54
	s_nop 0
	v_pk_mul_f32 v[0:1], v[16:17], v[182:183] op_sel_hi:[1,0]
	v_permlane32_swap_b32_e32 v53, v55
	v_pk_mul_f32 v[4:5], v[8:9], v[182:183] op_sel_hi:[1,0]
	v_pk_mul_f32 v[6:7], v[12:13], v[182:183] op_sel_hi:[1,0]
	v_pk_mul_f32 v[16:17], v[140:141], v[0:1]
	v_pk_mul_f32 v[0:1], v[18:19], v[182:183] op_sel_hi:[1,0]
	global_store_dwordx4 v[184:185], v[52:55], off offset:96
	v_pk_mul_f32 v[50:51], v[156:157], v[6:7]
	v_pk_mul_f32 v[6:7], v[14:15], v[182:183] op_sel_hi:[1,0]
	v_pk_mul_f32 v[54:55], v[152:153], v[4:5]
	v_pk_mul_f32 v[4:5], v[10:11], v[182:183] op_sel_hi:[1,0]
	v_pk_mul_f32 v[14:15], v[142:143], v[0:1]
	v_pk_mul_f32 v[0:1], v[20:21], v[182:183] op_sel_hi:[1,0]
	v_pk_mul_f32 v[52:53], v[154:155], v[4:5]
	v_pk_mul_f32 v[48:49], v[158:159], v[6:7]
	v_pk_mul_f32 v[12:13], v[136:137], v[0:1]
	v_pk_mul_f32 v[0:1], v[22:23], v[182:183] op_sel_hi:[1,0]
	v_cvt_pk_bf16_f32 v4, v54, v55
	v_cvt_pk_bf16_f32 v5, v52, v53
	v_cvt_pk_bf16_f32 v6, v50, v51
	v_cvt_pk_bf16_f32 v7, v48, v49
	v_pk_mul_f32 v[10:11], v[138:139], v[0:1]
	v_pk_mul_f32 v[0:1], v[24:25], v[182:183] op_sel_hi:[1,0]
	v_permlane32_swap_b32_e32 v4, v6
	v_permlane32_swap_b32_e32 v5, v7
	v_pk_mul_f32 v[8:9], v[132:133], v[0:1]
	v_pk_mul_f32 v[0:1], v[26:27], v[182:183] op_sel_hi:[1,0]
	global_store_dwordx4 v[144:145], v[4:7], off offset:32
	v_cvt_pk_bf16_f32 v18, v16, v17
	v_cvt_pk_bf16_f32 v19, v14, v15
	v_pk_mul_f32 v[6:7], v[134:135], v[0:1]
	v_pk_mul_f32 v[0:1], v[28:29], v[182:183] op_sel_hi:[1,0]
	v_cvt_pk_bf16_f32 v20, v12, v13
	v_pk_mul_f32 v[2:3], v[128:129], v[0:1]
	v_pk_mul_f32 v[0:1], v[30:31], v[182:183] op_sel_hi:[1,0]
	v_cvt_pk_bf16_f32 v21, v10, v11
	v_pk_mul_f32 v[0:1], v[130:131], v[0:1]
	v_cvt_pk_bf16_f32 v22, v8, v9
	v_cvt_pk_bf16_f32 v23, v6, v7
	v_cvt_pk_bf16_f32 v24, v2, v3
	v_cvt_pk_bf16_f32 v25, v0, v1
	v_permlane32_swap_b32_e32 v18, v20
	v_permlane32_swap_b32_e32 v19, v21
	v_permlane32_swap_b32_e32 v22, v24
	v_permlane32_swap_b32_e32 v23, v25
	global_store_dwordx4 v[144:145], v[18:21], off offset:64
	global_store_dwordx4 v[144:145], v[22:25], off offset:96
	s_and_saveexec_b64 s[4:5], vcc
	s_cbranch_execz .LBB0_235
	v_xor_b32_e32 v5, 1, v186
	v_cmp_lt_i32_e32 vcc, v5, v190
	s_nop 1
	v_cndmask_b32_e32 v5, v186, v5, vcc
	v_lshlrev_b32_e32 v18, 2, v5
	v_xor_b32_e32 v5, 2, v186
	v_cmp_lt_i32_e32 vcc, v5, v190
	s_nop 1
	v_cndmask_b32_e32 v5, v186, v5, vcc
	v_lshlrev_b32_e32 v19, 2, v5
	v_xor_b32_e32 v5, 4, v186
	v_cmp_lt_i32_e32 vcc, v5, v190
	s_nop 1
	v_cndmask_b32_e32 v5, v186, v5, vcc
	v_lshlrev_b32_e32 v20, 2, v5
	v_xor_b32_e32 v5, 8, v186
	v_cmp_lt_i32_e32 vcc, v5, v190
	s_nop 1
	v_cndmask_b32_e32 v5, v186, v5, vcc
	v_lshlrev_b32_e32 v21, 2, v5
	v_xor_b32_e32 v5, 16, v186
	v_cmp_lt_i32_e32 vcc, v5, v190
	s_nop 1
	v_cndmask_b32_e32 v5, v186, v5, vcc
	v_lshlrev_b32_e32 v22, 2, v5
	v_add_u32_e32 v23, 0xfffffe00, v164
	v_lshrrev_b32_e32 v24, 7, v189
	v_lshlrev_b32_e32 v25, 2, v187
	v_lshlrev_b32_e32 v160, 2, v25
	v_lshrrev_b32_e32 v4, 1, v23
	v_lshl_add_u32 v4, s30, 8, v4
	v_and_or_b32 v4, v24, 31, v4
	v_ashrrev_i32_e32 v5, 31, v4
	v_lshlrev_b64 v[4:5], 8, v[4:5]
	v_lshl_add_u64 v[4:5], s[28:29], 0, v[4:5]
	v_lshl_add_u64 v[24:25], v[4:5], 0, v[160:161]
	v_add_f32_e32 v178, 0, v178
	v_add_f32_e32 v178, v178, v126
	v_add_f32_e32 v178, v178, v94
	v_add_f32_e32 v178, v178, v62
	v_add_f32_e32 v179, 0, v179
	v_add_f32_e32 v179, v179, v127
	v_add_f32_e32 v179, v179, v95
	v_add_f32_e32 v179, v179, v63
	v_add_f32_e32 v176, 0, v176
	v_add_f32_e32 v176, v176, v124
	v_add_f32_e32 v176, v176, v92
	v_add_f32_e32 v176, v176, v60
	v_add_f32_e32 v177, 0, v177
	v_add_f32_e32 v177, v177, v125
	v_add_f32_e32 v177, v177, v93
	v_add_f32_e32 v177, v177, v61
	v_add_f32_e32 v174, 0, v174
	v_add_f32_e32 v174, v174, v122
	v_add_f32_e32 v174, v174, v90
	v_add_f32_e32 v174, v174, v58
	v_add_f32_e32 v175, 0, v175
	v_add_f32_e32 v175, v175, v123
	v_add_f32_e32 v175, v175, v91
	v_add_f32_e32 v175, v175, v59
	v_add_f32_e32 v172, 0, v172
	v_add_f32_e32 v172, v172, v120
	v_add_f32_e32 v172, v172, v88
	v_add_f32_e32 v172, v172, v56
	v_add_f32_e32 v173, 0, v173
	v_add_f32_e32 v173, v173, v121
	v_add_f32_e32 v173, v173, v89
	v_add_f32_e32 v173, v173, v57
	v_add_f32_e32 v170, 0, v170
	v_add_f32_e32 v170, v170, v118
	v_add_f32_e32 v170, v170, v86
	v_add_f32_e32 v170, v170, v54
	v_add_f32_e32 v171, 0, v171
	v_add_f32_e32 v171, v171, v119
	v_add_f32_e32 v171, v171, v87
	v_add_f32_e32 v171, v171, v55
	v_add_f32_e32 v168, 0, v168
	v_add_f32_e32 v168, v168, v116
	v_add_f32_e32 v168, v168, v84
	v_add_f32_e32 v168, v168, v52
	v_add_f32_e32 v169, 0, v169
	v_add_f32_e32 v169, v169, v117
	v_add_f32_e32 v169, v169, v85
	v_add_f32_e32 v169, v169, v53
	v_add_f32_e32 v166, 0, v166
	v_add_f32_e32 v166, v166, v114
	v_add_f32_e32 v166, v166, v82
	v_add_f32_e32 v166, v166, v50
	v_add_f32_e32 v167, 0, v167
	v_add_f32_e32 v167, v167, v115
	v_add_f32_e32 v167, v167, v83
	v_add_f32_e32 v167, v167, v51
	v_add_f32_e32 v162, 0, v162
	v_add_f32_e32 v162, v162, v112
	v_add_f32_e32 v162, v162, v80
	v_add_f32_e32 v162, v162, v48
	v_add_f32_e32 v163, 0, v163
	v_add_f32_e32 v163, v163, v113
	v_add_f32_e32 v163, v163, v81
	v_add_f32_e32 v163, v163, v49
	v_add_f32_e32 v110, 0, v110
	v_add_f32_e32 v110, v110, v78
	v_add_f32_e32 v110, v110, v46
	v_add_f32_e32 v110, v110, v16
	v_add_f32_e32 v111, 0, v111
	v_add_f32_e32 v111, v111, v79
	v_add_f32_e32 v111, v111, v47
	v_add_f32_e32 v111, v111, v17
	v_add_f32_e32 v108, 0, v108
	v_add_f32_e32 v108, v108, v76
	v_add_f32_e32 v108, v108, v44
	v_add_f32_e32 v108, v108, v14
	v_add_f32_e32 v109, 0, v109
	v_add_f32_e32 v109, v109, v77
	v_add_f32_e32 v109, v109, v45
	v_add_f32_e32 v109, v109, v15
	v_add_f32_e32 v106, 0, v106
	v_add_f32_e32 v106, v106, v74
	v_add_f32_e32 v106, v106, v42
	v_add_f32_e32 v106, v106, v12
	v_add_f32_e32 v107, 0, v107
	v_add_f32_e32 v107, v107, v75
	v_add_f32_e32 v107, v107, v43
	v_add_f32_e32 v107, v107, v13
	v_add_f32_e32 v104, 0, v104
	v_add_f32_e32 v104, v104, v72
	v_add_f32_e32 v104, v104, v40
	v_add_f32_e32 v104, v104, v10
	v_add_f32_e32 v105, 0, v105
	v_add_f32_e32 v105, v105, v73
	v_add_f32_e32 v105, v105, v41
	v_add_f32_e32 v105, v105, v11
	v_add_f32_e32 v102, 0, v102
	v_add_f32_e32 v102, v102, v70
	v_add_f32_e32 v102, v102, v38
	v_add_f32_e32 v102, v102, v8
	v_add_f32_e32 v103, 0, v103
	v_add_f32_e32 v103, v103, v71
	v_add_f32_e32 v103, v103, v39
	v_add_f32_e32 v103, v103, v9
	v_add_f32_e32 v100, 0, v100
	v_add_f32_e32 v100, v100, v68
	v_add_f32_e32 v100, v100, v36
	v_add_f32_e32 v100, v100, v6
	v_add_f32_e32 v101, 0, v101
	v_add_f32_e32 v101, v101, v69
	v_add_f32_e32 v101, v101, v37
	v_add_f32_e32 v101, v101, v7
	v_add_f32_e32 v98, 0, v98
	v_add_f32_e32 v98, v98, v66
	v_add_f32_e32 v98, v98, v34
	v_add_f32_e32 v98, v98, v2
	v_add_f32_e32 v99, 0, v99
	v_add_f32_e32 v99, v99, v67
	v_add_f32_e32 v99, v99, v35
	v_add_f32_e32 v99, v99, v3
	v_add_f32_e32 v96, 0, v96
	v_add_f32_e32 v96, v96, v64
	v_add_f32_e32 v96, v96, v32
	v_add_f32_e32 v96, v96, v0
	v_add_f32_e32 v97, 0, v97
	v_add_f32_e32 v97, v97, v65
	v_add_f32_e32 v97, v97, v33
	v_add_f32_e32 v97, v97, v1
	ds_bpermute_b32 v126, v18, v178
	ds_bpermute_b32 v127, v18, v179
	ds_bpermute_b32 v124, v18, v176
	ds_bpermute_b32 v125, v18, v177
	ds_bpermute_b32 v122, v18, v174
	ds_bpermute_b32 v123, v18, v175
	ds_bpermute_b32 v120, v18, v172
	ds_bpermute_b32 v121, v18, v173
	ds_bpermute_b32 v118, v18, v170
	ds_bpermute_b32 v119, v18, v171
	ds_bpermute_b32 v116, v18, v168
	ds_bpermute_b32 v117, v18, v169
	ds_bpermute_b32 v114, v18, v166
	ds_bpermute_b32 v115, v18, v167
	ds_bpermute_b32 v112, v18, v162
	ds_bpermute_b32 v113, v18, v163
	s_waitcnt lgkmcnt(0)
	v_add_f32_e32 v178, v178, v126
	v_add_f32_e32 v179, v179, v127
	v_add_f32_e32 v176, v176, v124
	v_add_f32_e32 v177, v177, v125
	v_add_f32_e32 v174, v174, v122
	v_add_f32_e32 v175, v175, v123
	v_add_f32_e32 v172, v172, v120
	v_add_f32_e32 v173, v173, v121
	v_add_f32_e32 v170, v170, v118
	v_add_f32_e32 v171, v171, v119
	v_add_f32_e32 v168, v168, v116
	v_add_f32_e32 v169, v169, v117
	v_add_f32_e32 v166, v166, v114
	v_add_f32_e32 v167, v167, v115
	v_add_f32_e32 v162, v162, v112
	v_add_f32_e32 v163, v163, v113
	ds_bpermute_b32 v78, v18, v110
	ds_bpermute_b32 v79, v18, v111
	ds_bpermute_b32 v76, v18, v108
	ds_bpermute_b32 v77, v18, v109
	ds_bpermute_b32 v74, v18, v106
	ds_bpermute_b32 v75, v18, v107
	ds_bpermute_b32 v72, v18, v104
	ds_bpermute_b32 v73, v18, v105
	ds_bpermute_b32 v70, v18, v102
	ds_bpermute_b32 v71, v18, v103
	ds_bpermute_b32 v68, v18, v100
	ds_bpermute_b32 v69, v18, v101
	ds_bpermute_b32 v66, v18, v98
	ds_bpermute_b32 v67, v18, v99
	ds_bpermute_b32 v64, v18, v96
	ds_bpermute_b32 v65, v18, v97
	s_waitcnt lgkmcnt(0)
	v_add_f32_e32 v110, v110, v78
	v_add_f32_e32 v111, v111, v79
	v_add_f32_e32 v108, v108, v76
	v_add_f32_e32 v109, v109, v77
	v_add_f32_e32 v106, v106, v74
	v_add_f32_e32 v107, v107, v75
	v_add_f32_e32 v104, v104, v72
	v_add_f32_e32 v105, v105, v73
	v_add_f32_e32 v102, v102, v70
	v_add_f32_e32 v103, v103, v71
	v_add_f32_e32 v100, v100, v68
	v_add_f32_e32 v101, v101, v69
	v_add_f32_e32 v98, v98, v66
	v_add_f32_e32 v99, v99, v67
	v_add_f32_e32 v96, v96, v64
	v_add_f32_e32 v97, v97, v65
	ds_bpermute_b32 v126, v19, v178
	ds_bpermute_b32 v127, v19, v179
	ds_bpermute_b32 v124, v19, v176
	ds_bpermute_b32 v125, v19, v177
	ds_bpermute_b32 v122, v19, v174
	ds_bpermute_b32 v123, v19, v175
	ds_bpermute_b32 v120, v19, v172
	ds_bpermute_b32 v121, v19, v173
	ds_bpermute_b32 v118, v19, v170
	ds_bpermute_b32 v119, v19, v171
	ds_bpermute_b32 v116, v19, v168
	ds_bpermute_b32 v117, v19, v169
	ds_bpermute_b32 v114, v19, v166
	ds_bpermute_b32 v115, v19, v167
	ds_bpermute_b32 v112, v19, v162
	ds_bpermute_b32 v113, v19, v163
	s_waitcnt lgkmcnt(0)
	v_add_f32_e32 v178, v178, v126
	v_add_f32_e32 v179, v179, v127
	v_add_f32_e32 v176, v176, v124
	v_add_f32_e32 v177, v177, v125
	v_add_f32_e32 v174, v174, v122
	v_add_f32_e32 v175, v175, v123
	v_add_f32_e32 v172, v172, v120
	v_add_f32_e32 v173, v173, v121
	v_add_f32_e32 v170, v170, v118
	v_add_f32_e32 v171, v171, v119
	v_add_f32_e32 v168, v168, v116
	v_add_f32_e32 v169, v169, v117
	v_add_f32_e32 v166, v166, v114
	v_add_f32_e32 v167, v167, v115
	v_add_f32_e32 v162, v162, v112
	v_add_f32_e32 v163, v163, v113
	ds_bpermute_b32 v78, v19, v110
	ds_bpermute_b32 v79, v19, v111
	ds_bpermute_b32 v76, v19, v108
	ds_bpermute_b32 v77, v19, v109
	ds_bpermute_b32 v74, v19, v106
	ds_bpermute_b32 v75, v19, v107
	ds_bpermute_b32 v72, v19, v104
	ds_bpermute_b32 v73, v19, v105
	ds_bpermute_b32 v70, v19, v102
	ds_bpermute_b32 v71, v19, v103
	ds_bpermute_b32 v68, v19, v100
	ds_bpermute_b32 v69, v19, v101
	ds_bpermute_b32 v66, v19, v98
	ds_bpermute_b32 v67, v19, v99
	ds_bpermute_b32 v64, v19, v96
	ds_bpermute_b32 v65, v19, v97
	s_waitcnt lgkmcnt(0)
	v_add_f32_e32 v110, v110, v78
	v_add_f32_e32 v111, v111, v79
	v_add_f32_e32 v108, v108, v76
	v_add_f32_e32 v109, v109, v77
	v_add_f32_e32 v106, v106, v74
	v_add_f32_e32 v107, v107, v75
	v_add_f32_e32 v104, v104, v72
	v_add_f32_e32 v105, v105, v73
	v_add_f32_e32 v102, v102, v70
	v_add_f32_e32 v103, v103, v71
	v_add_f32_e32 v100, v100, v68
	v_add_f32_e32 v101, v101, v69
	v_add_f32_e32 v98, v98, v66
	v_add_f32_e32 v99, v99, v67
	v_add_f32_e32 v96, v96, v64
	v_add_f32_e32 v97, v97, v65
	ds_bpermute_b32 v126, v20, v178
	ds_bpermute_b32 v127, v20, v179
	ds_bpermute_b32 v124, v20, v176
	ds_bpermute_b32 v125, v20, v177
	ds_bpermute_b32 v122, v20, v174
	ds_bpermute_b32 v123, v20, v175
	ds_bpermute_b32 v120, v20, v172
	ds_bpermute_b32 v121, v20, v173
	ds_bpermute_b32 v118, v20, v170
	ds_bpermute_b32 v119, v20, v171
	ds_bpermute_b32 v116, v20, v168
	ds_bpermute_b32 v117, v20, v169
	ds_bpermute_b32 v114, v20, v166
	ds_bpermute_b32 v115, v20, v167
	ds_bpermute_b32 v112, v20, v162
	ds_bpermute_b32 v113, v20, v163
	s_waitcnt lgkmcnt(0)
	v_add_f32_e32 v178, v178, v126
	v_add_f32_e32 v179, v179, v127
	v_add_f32_e32 v176, v176, v124
	v_add_f32_e32 v177, v177, v125
	v_add_f32_e32 v174, v174, v122
	v_add_f32_e32 v175, v175, v123
	v_add_f32_e32 v172, v172, v120
	v_add_f32_e32 v173, v173, v121
	v_add_f32_e32 v170, v170, v118
	v_add_f32_e32 v171, v171, v119
	v_add_f32_e32 v168, v168, v116
	v_add_f32_e32 v169, v169, v117
	v_add_f32_e32 v166, v166, v114
	v_add_f32_e32 v167, v167, v115
	v_add_f32_e32 v162, v162, v112
	v_add_f32_e32 v163, v163, v113
	ds_bpermute_b32 v78, v20, v110
	ds_bpermute_b32 v79, v20, v111
	ds_bpermute_b32 v76, v20, v108
	ds_bpermute_b32 v77, v20, v109
	ds_bpermute_b32 v74, v20, v106
	ds_bpermute_b32 v75, v20, v107
	ds_bpermute_b32 v72, v20, v104
	ds_bpermute_b32 v73, v20, v105
	ds_bpermute_b32 v70, v20, v102
	ds_bpermute_b32 v71, v20, v103
	ds_bpermute_b32 v68, v20, v100
	ds_bpermute_b32 v69, v20, v101
	ds_bpermute_b32 v66, v20, v98
	ds_bpermute_b32 v67, v20, v99
	ds_bpermute_b32 v64, v20, v96
	ds_bpermute_b32 v65, v20, v97
	s_waitcnt lgkmcnt(0)
	v_add_f32_e32 v110, v110, v78
	v_add_f32_e32 v111, v111, v79
	v_add_f32_e32 v108, v108, v76
	v_add_f32_e32 v109, v109, v77
	v_add_f32_e32 v106, v106, v74
	v_add_f32_e32 v107, v107, v75
	v_add_f32_e32 v104, v104, v72
	v_add_f32_e32 v105, v105, v73
	v_add_f32_e32 v102, v102, v70
	v_add_f32_e32 v103, v103, v71
	v_add_f32_e32 v100, v100, v68
	v_add_f32_e32 v101, v101, v69
	v_add_f32_e32 v98, v98, v66
	v_add_f32_e32 v99, v99, v67
	v_add_f32_e32 v96, v96, v64
	v_add_f32_e32 v97, v97, v65
	ds_bpermute_b32 v126, v21, v178
	ds_bpermute_b32 v127, v21, v179
	ds_bpermute_b32 v124, v21, v176
	ds_bpermute_b32 v125, v21, v177
	ds_bpermute_b32 v122, v21, v174
	ds_bpermute_b32 v123, v21, v175
	ds_bpermute_b32 v120, v21, v172
	ds_bpermute_b32 v121, v21, v173
	ds_bpermute_b32 v118, v21, v170
	ds_bpermute_b32 v119, v21, v171
	ds_bpermute_b32 v116, v21, v168
	ds_bpermute_b32 v117, v21, v169
	ds_bpermute_b32 v114, v21, v166
	ds_bpermute_b32 v115, v21, v167
	ds_bpermute_b32 v112, v21, v162
	ds_bpermute_b32 v113, v21, v163
	s_waitcnt lgkmcnt(0)
	v_add_f32_e32 v178, v178, v126
	v_add_f32_e32 v179, v179, v127
	v_add_f32_e32 v176, v176, v124
	v_add_f32_e32 v177, v177, v125
	v_add_f32_e32 v174, v174, v122
	v_add_f32_e32 v175, v175, v123
	v_add_f32_e32 v172, v172, v120
	v_add_f32_e32 v173, v173, v121
	v_add_f32_e32 v170, v170, v118
	v_add_f32_e32 v171, v171, v119
	v_add_f32_e32 v168, v168, v116
	v_add_f32_e32 v169, v169, v117
	v_add_f32_e32 v166, v166, v114
	v_add_f32_e32 v167, v167, v115
	v_add_f32_e32 v162, v162, v112
	v_add_f32_e32 v163, v163, v113
	ds_bpermute_b32 v78, v21, v110
	ds_bpermute_b32 v79, v21, v111
	ds_bpermute_b32 v76, v21, v108
	ds_bpermute_b32 v77, v21, v109
	ds_bpermute_b32 v74, v21, v106
	ds_bpermute_b32 v75, v21, v107
	ds_bpermute_b32 v72, v21, v104
	ds_bpermute_b32 v73, v21, v105
	ds_bpermute_b32 v70, v21, v102
	ds_bpermute_b32 v71, v21, v103
	ds_bpermute_b32 v68, v21, v100
	ds_bpermute_b32 v69, v21, v101
	ds_bpermute_b32 v66, v21, v98
	ds_bpermute_b32 v67, v21, v99
	ds_bpermute_b32 v64, v21, v96
	ds_bpermute_b32 v65, v21, v97
	s_waitcnt lgkmcnt(0)
	v_add_f32_e32 v110, v110, v78
	v_add_f32_e32 v111, v111, v79
	v_add_f32_e32 v108, v108, v76
	v_add_f32_e32 v109, v109, v77
	v_add_f32_e32 v106, v106, v74
	v_add_f32_e32 v107, v107, v75
	v_add_f32_e32 v104, v104, v72
	v_add_f32_e32 v105, v105, v73
	v_add_f32_e32 v102, v102, v70
	v_add_f32_e32 v103, v103, v71
	v_add_f32_e32 v100, v100, v68
	v_add_f32_e32 v101, v101, v69
	v_add_f32_e32 v98, v98, v66
	v_add_f32_e32 v99, v99, v67
	v_add_f32_e32 v96, v96, v64
	v_add_f32_e32 v97, v97, v65
	ds_bpermute_b32 v126, v22, v178
	ds_bpermute_b32 v127, v22, v179
	ds_bpermute_b32 v124, v22, v176
	ds_bpermute_b32 v125, v22, v177
	ds_bpermute_b32 v122, v22, v174
	ds_bpermute_b32 v123, v22, v175
	ds_bpermute_b32 v120, v22, v172
	ds_bpermute_b32 v121, v22, v173
	ds_bpermute_b32 v118, v22, v170
	ds_bpermute_b32 v119, v22, v171
	ds_bpermute_b32 v116, v22, v168
	ds_bpermute_b32 v117, v22, v169
	ds_bpermute_b32 v114, v22, v166
	ds_bpermute_b32 v115, v22, v167
	ds_bpermute_b32 v112, v22, v162
	ds_bpermute_b32 v113, v22, v163
	s_waitcnt lgkmcnt(0)
	v_add_f32_e32 v178, v178, v126
	v_add_f32_e32 v179, v179, v127
	v_add_f32_e32 v176, v176, v124
	v_add_f32_e32 v177, v177, v125
	v_add_f32_e32 v174, v174, v122
	v_add_f32_e32 v175, v175, v123
	v_add_f32_e32 v172, v172, v120
	v_add_f32_e32 v173, v173, v121
	v_add_f32_e32 v170, v170, v118
	v_add_f32_e32 v171, v171, v119
	v_add_f32_e32 v168, v168, v116
	v_add_f32_e32 v169, v169, v117
	v_add_f32_e32 v166, v166, v114
	v_add_f32_e32 v167, v167, v115
	v_add_f32_e32 v162, v162, v112
	v_add_f32_e32 v163, v163, v113
	ds_bpermute_b32 v78, v22, v110
	ds_bpermute_b32 v79, v22, v111
	ds_bpermute_b32 v76, v22, v108
	ds_bpermute_b32 v77, v22, v109
	ds_bpermute_b32 v74, v22, v106
	ds_bpermute_b32 v75, v22, v107
	ds_bpermute_b32 v72, v22, v104
	ds_bpermute_b32 v73, v22, v105
	ds_bpermute_b32 v70, v22, v102
	ds_bpermute_b32 v71, v22, v103
	ds_bpermute_b32 v68, v22, v100
	ds_bpermute_b32 v69, v22, v101
	ds_bpermute_b32 v66, v22, v98
	ds_bpermute_b32 v67, v22, v99
	ds_bpermute_b32 v64, v22, v96
	ds_bpermute_b32 v65, v22, v97
	s_waitcnt lgkmcnt(0)
	v_add_f32_e32 v110, v110, v78
	v_add_f32_e32 v111, v111, v79
	v_add_f32_e32 v108, v108, v76
	v_add_f32_e32 v109, v109, v77
	v_add_f32_e32 v106, v106, v74
	v_add_f32_e32 v107, v107, v75
	v_add_f32_e32 v104, v104, v72
	v_add_f32_e32 v105, v105, v73
	v_add_f32_e32 v102, v102, v70
	v_add_f32_e32 v103, v103, v71
	v_add_f32_e32 v100, v100, v68
	v_add_f32_e32 v101, v101, v69
	v_add_f32_e32 v98, v98, v66
	v_add_f32_e32 v99, v99, v67
	v_add_f32_e32 v96, v96, v64
	v_add_f32_e32 v97, v97, v65
	v_cmp_eq_u32_e32 vcc, 0, v188
	s_and_saveexec_b64 s[62:63], vcc
	s_cbranch_execz .Lksum_done
	global_store_dword v[24:25], v178, off
	global_store_dword v[24:25], v179, off offset:4
	global_store_dword v[24:25], v176, off offset:8
	global_store_dword v[24:25], v177, off offset:12
	global_store_dword v[24:25], v174, off offset:32
	global_store_dword v[24:25], v175, off offset:36
	global_store_dword v[24:25], v172, off offset:40
	global_store_dword v[24:25], v173, off offset:44
	global_store_dword v[24:25], v170, off offset:64
	global_store_dword v[24:25], v171, off offset:68
	global_store_dword v[24:25], v168, off offset:72
	global_store_dword v[24:25], v169, off offset:76
	global_store_dword v[24:25], v166, off offset:96
	global_store_dword v[24:25], v167, off offset:100
	global_store_dword v[24:25], v162, off offset:104
	global_store_dword v[24:25], v163, off offset:108
	global_store_dword v[24:25], v110, off offset:128
	global_store_dword v[24:25], v111, off offset:132
	global_store_dword v[24:25], v108, off offset:136
	global_store_dword v[24:25], v109, off offset:140
	global_store_dword v[24:25], v106, off offset:160
	global_store_dword v[24:25], v107, off offset:164
	global_store_dword v[24:25], v104, off offset:168
	global_store_dword v[24:25], v105, off offset:172
	global_store_dword v[24:25], v102, off offset:192
	global_store_dword v[24:25], v103, off offset:196
	global_store_dword v[24:25], v100, off offset:200
	global_store_dword v[24:25], v101, off offset:204
	global_store_dword v[24:25], v98, off offset:224
	global_store_dword v[24:25], v99, off offset:228
	global_store_dword v[24:25], v96, off offset:232
	global_store_dword v[24:25], v97, off offset:236
.Lksum_done:
	s_or_b64 exec, exec, s[62:63]
	s_branch .LBB0_235
